# baseline (speedup 1.0000x reference)
; DI int get_bid() { int b = blockIdx.x; asm volatile("" : "+s"(b)); return b; }
; DI int get_tid_(int wv) { int z = 0; asm volatile("" : "+v"(z)); asm volatile("" : "+s"(wv)); const int lane = __builtin_amdgcn_mbcnt_hi(~0u, __builtin_amdgcn_mbcnt_lo(~0u, z)); return (wv << 6) | lane; }
; #define RW_LOAD(r_) do { _Pragma("unroll") for (int j = 0; j < 4; ++j) { xn[j] = *(const f32x4*)(xsrc + ((size_t)b * S_ + (r_)) * 1024 + j * 256 + lane * 4); \
;         if (has_post) tn[j] = *(const u32x2*)(p.proj + (size_t)(r_) * LDP + j * 256 + lane * 4); } } while (0)
; DI void rowwise(const PP& p, int l, int b, int mode, char* lds) {
;     const int tid = get_tid_(p.wv), wid = tid >> 6, lane = tid & 63;
;     const bool has_post = mode != 0, has_pre = mode != 3, has_ff = (mode == 0 || mode == 2);
;     const int lp = (mode == 2) ? l - 1 : l;
;     const float* gate = p.mod + ((size_t)(lp * 2 + b) * 6 + (mode == 1 ? 2 : 5)) * 1024;
;     const float* gpost = (mode == 1 ? p.g_post_mix : p.g_post_mlp) + lp * 1024;
;     const float* gpre = (mode == 1 ? p.g_pre_mlp : p.g_pre_mix) + l * 1024;
;     const float* shp = p.mod + ((size_t)(l * 2 + b) * 6 + (mode == 1 ? 3 : 0)) * 1024;
;     const float* scp = shp + 1024;
;     const float* xsrc = (mode == 0 || (mode == 1 && l == 0)) ? p.x : p.out;
;     float* wl = (float*)lds;
;     __syncthreads();
;     if (has_ff) {
; #pragma unroll
;         for (int i = 0; i < 4; ++i) *(f32x4*)(wl + (tid + 512 * i) * 4) = *(const f32x4*)(p.wff + (size_t)l * 8192 + (tid + 512 * i) * 4);
;     }
;     __syncthreads();
;     const int row0 = get_bid() * 8 + wid, rstride = gridDim.x * 8;
;     f32x4 xn[4]; u32x2 tn[4];
;     ...
;     if (row0 < S_) RW_LOAD(row0);
;     for (int row = row0; row < S_; row += rstride) {
;         const size_t tok = (size_t)b * S_ + row;
;         f32x4 xv[4]; u32x2 tw[4];
; #pragma unroll
;         for (int j = 0; j < 4; ++j) { xv[j] = xn[j]; tw[j] = tn[j]; }
;         if (row + rstride < S_) RW_LOAD(row + rstride);
.LBB0_26:
	s_mov_b64 s[2:3], 0
	v_writelane_b32 v255, s2, 25
	s_waitcnt vmcnt(6)
	v_cndmask_b32_e64 v156, 0, 1, s[90:91]
	s_mov_b64 s[0:1], -1
	v_writelane_b32 v255, s3, 26
	v_readfirstlane_b32 s33, v156
	s_mov_b64 s[30:31], 0
	s_cmp_lt_i32 s29, 5
	s_mov_b64 s[88:89], 0
	v_writelane_b32 v255, s22, 27
	s_cbranch_scc1 .LBB0_129
	s_cmp_gt_i32 s29, 6
	s_cbranch_scc0 .LBB0_36
	s_cmp_gt_i32 s29, 7
	s_cbranch_scc0 .LBB0_37
	s_mov_b64 s[4:5], 0
	v_writelane_b32 v255, s4, 25
	s_cmp_gt_i32 s29, 8
	s_nop 0
	v_writelane_b32 v255, s5, 26
	s_cbranch_scc0 .LBB0_39
	v_writelane_b32 v255, s0, 25
	s_cmp_eq_u32 s29, 9
	s_nop 0
	v_writelane_b32 v255, s1, 26
	s_cbranch_scc0 .LBB0_38
	v_mov_b32_e32 v0, v1
	s_mov_b32 s0, s64
	v_mbcnt_lo_u32_b32 v0, -1, v0
	v_mbcnt_hi_u32_b32 v14, -1, v0
	v_lshl_or_b32 v0, s0, 6, v14
	v_readlane_b32 s0, v253, 0
	v_ashrrev_i32_e32 v0, 6, v0
	s_barrier
	s_barrier
	s_nop 0
	v_lshl_add_u32 v38, s0, 3, v0
	s_movk_i32 s0, 0x4000
	v_cmp_gt_i32_e32 vcc, s0, v38
	s_and_saveexec_b64 s[4:5], vcc
	s_cbranch_execz .LBB0_65
	s_load_dword s12, s[24:25], 0x0
	s_add_i32 s0, s94, 2
	s_mul_hi_i32 s1, s0, 0x6000
	s_mulk_i32 s0, 0x6000
	s_mov_b64 s[86:87], s[62:63]
	s_waitcnt lgkmcnt(0)
	s_lshl_b32 s6, s12, 3
	s_add_u32 s0, s50, s0
	s_addc_u32 s1, s51, s1
	s_add_u32 s8, s0, 0x5000
	s_addc_u32 s9, s1, 0
	s_ashr_i32 s95, s94, 31
	s_mov_b64 s[84:85], s[60:61]
	s_mov_b64 s[82:83], s[58:59]
	s_mov_b64 s[80:81], s[56:57]
	s_mov_b64 s[78:79], s[54:55]
	s_mov_b64 s[76:77], s[52:53]
	s_mov_b64 s[74:75], s[50:51]
	s_mov_b64 s[72:73], s[48:49]
	v_readlane_b32 s48, v254, 34
	s_lshl_b64 s[0:1], s[94:95], 26
	v_readlane_b32 s62, v254, 48
	v_readlane_b32 s49, v254, 35
	v_readlane_b32 s50, v254, 36
	v_readlane_b32 s51, v254, 37
	v_readlane_b32 s52, v254, 38
	v_readlane_b32 s53, v254, 39
	v_readlane_b32 s54, v254, 40
	v_readlane_b32 s55, v254, 41
	v_readlane_b32 s56, v254, 42
	v_readlane_b32 s57, v254, 43
	v_readlane_b32 s58, v254, 44
	v_readlane_b32 s59, v254, 45
	v_readlane_b32 s60, v254, 46
	v_readlane_b32 s61, v254, 47
	v_readlane_b32 s63, v254, 49
	s_add_u32 s0, s62, s0
	s_addc_u32 s1, s63, s1
	s_mov_b64 s[48:49], s[72:73]
	v_ashrrev_i32_e32 v39, 31, v38
	s_mov_b64 s[50:51], s[74:75]
	s_mov_b64 s[52:53], s[76:77]
	s_mov_b64 s[54:55], s[78:79]
	s_mov_b64 s[56:57], s[80:81]
	s_mov_b64 s[58:59], s[82:83]
	s_mov_b64 s[60:61], s[84:85]
	s_mov_b64 s[62:63], s[86:87]
	v_readlane_b32 s72, v255, 8
	v_lshlrev_b32_e32 v0, 2, v14
	v_readlane_b32 s86, v255, 22
	v_readlane_b32 s87, v255, 23
	v_lshlrev_b64 v[2:3], 12, v[38:39]
	v_and_b32_e32 v4, 0xfc, v0
	v_lshl_add_u64 v[40:41], s[0:1], 0, v[2:3]
	v_lshlrev_b32_e32 v0, 2, v4
	v_mov_b64_e32 v[2:3], s[86:87]
	v_lshl_add_u64 v[6:7], v[40:41], 0, v[0:1]
	v_mad_i64_i32 v[2:3], s[10:11], v38, s35, v[2:3]
	v_lshlrev_b32_e32 v4, 1, v4
	v_mov_b32_e32 v5, v1
	v_lshl_add_u64 v[16:17], v[2:3], 0, v[4:5]
	global_load_dwordx4 v[30:33], v[6:7], off
	global_load_dwordx2 v[72:73], v[16:17], off
	global_load_dwordx4 v[10:13], v[6:7], off offset:1024
	global_load_dwordx2 v[70:71], v[16:17], off offset:512
	global_load_dwordx4 v[2:5], v[6:7], off offset:2048
	global_load_dwordx2 v[36:37], v[16:17], off offset:1024
	s_nop 0
	global_load_dwordx4 v[6:9], v[6:7], off offset:3072
	s_nop 0
	global_load_dwordx2 v[34:35], v[16:17], off offset:1536
	v_readlane_b32 s10, v253, 19
	v_readlane_b32 s11, v253, 20
	v_or_b32_e32 v16, 0x400, v0
	v_mov_b32_e32 v17, v1
	v_lshl_add_u64 v[46:47], s[8:9], 0, v[16:17]
	v_lshl_add_u64 v[48:49], s[10:11], 0, v[16:17]
	v_or_b32_e32 v16, 0x800, v0
	v_lshl_add_u64 v[42:43], s[8:9], 0, v[0:1]
	v_lshl_add_u64 v[44:45], s[10:11], 0, v[0:1]
	v_lshl_add_u64 v[50:51], s[8:9], 0, v[16:17]
	v_lshl_add_u64 v[52:53], s[10:11], 0, v[16:17]
	v_or_b32_e32 v0, 0xc00, v0
	v_add_u32_e32 v16, s6, v38
	v_lshl_add_u64 v[54:55], s[8:9], 0, v[0:1]
	v_lshl_add_u64 v[56:57], s[10:11], 0, v[0:1]
	v_ashrrev_i32_e32 v17, 31, v16
	v_mad_i64_i32 v[18:19], s[8:9], v16, s35, 0
	v_and_b32_e32 v0, 63, v14
	v_lshl_or_b32 v18, v0, 3, v18
	v_lshlrev_b64 v[14:15], 12, v[16:17]
	v_lshl_add_u64 v[58:59], s[86:87], 0, v[18:19]
	s_ashr_i32 s7, s6, 31
	v_lshl_add_u64 v[60:61], s[0:1], 0, v[14:15]
	v_readlane_b32 s73, v255, 9
	v_readlane_b32 s74, v255, 10
	v_readlane_b32 s75, v255, 11
	v_readlane_b32 s76, v255, 12
	v_readlane_b32 s77, v255, 13
	v_readlane_b32 s78, v255, 14
	v_readlane_b32 s79, v255, 15
	v_readlane_b32 s80, v255, 16
	v_readlane_b32 s81, v255, 17
	v_readlane_b32 s82, v255, 18
	v_readlane_b32 s83, v255, 19
	v_readlane_b32 s84, v255, 20
	v_readlane_b32 s85, v255, 21
	s_mul_i32 s8, s12, 0x2c000
	s_mul_hi_i32 s9, s6, 0x5800
	v_lshlrev_b32_e32 v0, 4, v0
	s_lshl_b64 s[10:11], s[6:7], 12
	s_mov_b64 s[12:13], 0
	s_waitcnt vmcnt(7)
	v_mov_b64_e32 v[14:15], v[30:31]
	s_waitcnt vmcnt(6)
	v_mov_b64_e32 v[62:63], v[72:73]
	s_waitcnt vmcnt(5)
	v_mov_b64_e32 v[20:21], v[12:13]
	s_waitcnt vmcnt(4)
	v_mov_b64_e32 v[64:65], v[70:71]
	s_waitcnt vmcnt(3)
	v_mov_b64_e32 v[24:25], v[4:5]
	s_waitcnt vmcnt(2)
	v_mov_b64_e32 v[66:67], v[36:37]
	s_waitcnt vmcnt(1)
	v_mov_b64_e32 v[28:29], v[8:9]
	s_waitcnt vmcnt(0)
	v_mov_b64_e32 v[68:69], v[34:35]
	v_mov_b64_e32 v[16:17], v[32:33]
	v_mov_b64_e32 v[18:19], v[10:11]
	v_mov_b64_e32 v[22:23], v[2:3]
	v_mov_b64_e32 v[26:27], v[6:7]
	global_load_dwordx4 v[108:111], v[42:43], off
	global_load_dwordx4 v[112:115], v[44:45], off
	global_load_dwordx4 v[116:119], v[46:47], off
	global_load_dwordx4 v[120:123], v[48:49], off
	global_load_dwordx4 v[124:127], v[50:51], off
	global_load_dwordx4 v[128:131], v[52:53], off
	global_load_dwordx4 v[132:135], v[54:55], off
	global_load_dwordx4 v[136:139], v[56:57], off
	s_waitcnt vmcnt(0)
	s_branch .LBB0_34
; DI float bflo(unsigned w) { return __uint_as_float(w << 16); }
; DI float bfhi(unsigned w) { return __uint_as_float(w & 0xffff0000u); }
; #define RW_LOAD(r_) do { _Pragma("unroll") for (int j = 0; j < 4; ++j) { xn[j] = *(const f32x4*)(xsrc + ((size_t)b * S_ + (r_)) * 1024 + j * 256 + lane * 4); \
;         if (has_post) tn[j] = *(const u32x2*)(p.proj + (size_t)(r_) * LDP + j * 256 + lane * 4); } } while (0)
; DI void rowwise(const PP& p, int l, int b, int mode, char* lds) {
;     ...
;     for (int row = row0; row < S_; row += rstride) {
;         const size_t tok = (size_t)b * S_ + row;
;         f32x4 xv[4]; u32x2 tw[4];
; #pragma unroll
;         for (int j = 0; j < 4; ++j) { xv[j] = xn[j]; tw[j] = tn[j]; }
;         if (row + rstride < S_) RW_LOAD(row + rstride);
;         if (has_post) {
;             f32x4 tv[4]; float ss = 0.f;
; #pragma unroll
;             for (int j = 0; j < 4; ++j) {
;                 const u32x2 w = tw[j];
;                 tv[j] = (f32x4){bflo(w.x), bfhi(w.x), bflo(w.y), bfhi(w.y)};
;                 ss += tv[j][0] * tv[j][0] + tv[j][1] * tv[j][1] + tv[j][2] * tv[j][2] + tv[j][3] * tv[j][3];
;             }
;             ss = wave_sum(ss);
;             const float rstd = rsqrtf(ss * (1.f / 1024.f) + 1e-6f);
; #pragma unroll
;             for (int j = 0; j < 4; ++j) {
;                 const int c = j * 256 + lane * 4;
;                 const f32x4 g = *(const f32x4*)(gate + c), gp = *(const f32x4*)(gpost + c);
;                 xv[j] += g * (tv[j] * rstd * gp);
;                 *(f32x4*)(p.out + tok * 1024 + c) = xv[j];
;             }
.LBB0_33:
	s_or_b64 exec, exec, s[14:15]
	v_and_b32_e32 v85, 0xffff0000, v72
	v_and_b32_e32 v83, 0xffff0000, v70
	v_lshlrev_b32_e32 v84, 16, v72
	v_mul_f32_e32 v39, v85, v85
	v_lshlrev_b32_e32 v82, 16, v70
	v_mul_f32_e32 v70, v83, v83
	v_lshlrev_b32_e32 v86, 16, v73
	v_fmac_f32_e32 v39, v84, v84
	v_lshlrev_b32_e32 v80, 16, v71
	v_fmac_f32_e32 v70, v82, v82
	v_and_b32_e32 v87, 0xffff0000, v73
	v_fmac_f32_e32 v39, v86, v86
	v_and_b32_e32 v81, 0xffff0000, v71
	v_fmac_f32_e32 v70, v80, v80
	v_and_b32_e32 v77, 0xffff0000, v36
	v_fmac_f32_e32 v39, v87, v87
	v_fmac_f32_e32 v70, v81, v81
	v_lshlrev_b32_e32 v76, 16, v36
	v_mul_f32_e32 v36, v77, v77
	v_and_b32_e32 v71, 0xffff0000, v34
	v_add_f32_e32 v39, v39, v70
	v_lshlrev_b32_e32 v74, 16, v37
	v_fmac_f32_e32 v36, v76, v76
	v_lshlrev_b32_e32 v70, 16, v34
	v_mul_f32_e32 v34, v71, v71
	v_and_b32_e32 v75, 0xffff0000, v37
	v_fmac_f32_e32 v36, v74, v74
	v_lshlrev_b32_e32 v72, 16, v35
	v_fmac_f32_e32 v34, v70, v70
	v_fmac_f32_e32 v36, v75, v75
	v_and_b32_e32 v73, 0xffff0000, v35
	v_fmac_f32_e32 v34, v72, v72
	v_add_f32_e32 v36, v39, v36
	v_fmac_f32_e32 v34, v73, v73
	v_add_f32_e32 v34, v36, v34
	s_and_b64 s[0:1], exec, vcc
	s_or_b64 s[12:13], s[0:1], s[12:13]
	v_add_f32_dpp v34, v34, v34 quad_perm:[1,0,3,2] row_mask:0xf bank_mask:0xf bound_ctrl:1
	v_lshl_add_u64 v[58:59], v[58:59], 0, s[8:9]
	v_lshl_add_u64 v[60:61], v[60:61], 0, s[10:11]
	v_add_f32_dpp v34, v34, v34 quad_perm:[2,3,0,1] row_mask:0xf bank_mask:0xf bound_ctrl:1
	ds_swizzle_b32 v35, v34 offset:swizzle(SWAP,4)
	s_waitcnt lgkmcnt(0)
	v_add_f32_e32 v34, v34, v35
	ds_swizzle_b32 v35, v34 offset:swizzle(SWAP,8)
	s_waitcnt lgkmcnt(0)
	v_add_f32_e32 v34, v34, v35
	ds_swizzle_b32 v35, v34 offset:swizzle(SWAP,16)
	s_waitcnt lgkmcnt(0)
	v_add_f32_e32 v34, v34, v35
	v_mov_b32_e32 v35, v34
	s_nop 1
	v_permlane32_swap_b32_e32 v34, v35
	v_add_f32_e32 v34, v34, v35
	v_fmamk_f32 v34, v34, 0x3a800000, v217
	v_cmp_gt_f32_e32 vcc, s66, v34
	v_mul_f32_e32 v35, 0x4b800000, v34
	s_nop 0
	v_cndmask_b32_e32 v34, v34, v35, vcc
	v_rsq_f32_e32 v34, v34
	s_nop 0
	v_mul_f32_e32 v35, 0x45800000, v34
	v_cndmask_b32_e32 v78, v34, v35, vcc
	v_pk_mul_f32 v[86:87], v[86:87], v[78:79] op_sel_hi:[1,0]
	v_pk_mul_f32 v[84:85], v[84:85], v[78:79] op_sel_hi:[1,0]
	v_pk_mul_f32 v[82:83], v[82:83], v[78:79] op_sel_hi:[1,0]
	v_pk_mul_f32 v[80:81], v[80:81], v[78:79] op_sel_hi:[1,0]
	v_mov_b64_e32 v[34:35], v[108:109]
	v_mov_b64_e32 v[36:37], v[110:111]
	v_mov_b64_e32 v[88:89], v[112:113]
	v_mov_b64_e32 v[90:91], v[114:115]
	v_pk_mul_f32 v[84:85], v[88:89], v[84:85]
	v_pk_mul_f32 v[86:87], v[90:91], v[86:87]
	v_pk_fma_f32 v[30:31], v[34:35], v[84:85], v[30:31]
	v_pk_fma_f32 v[32:33], v[36:37], v[86:87], v[32:33]
	v_lshl_add_u64 v[84:85], v[40:41], 0, v[0:1]
	global_store_dwordx4 v[84:85], v[30:33], off
	s_nop 0
	v_lshl_add_u64 v[40:41], v[40:41], 0, s[10:11]
	v_mov_b64_e32 v[30:31], v[116:117]
	v_mov_b64_e32 v[32:33], v[118:119]
	v_mov_b64_e32 v[34:35], v[120:121]
	v_mov_b64_e32 v[36:37], v[122:123]
	v_pk_mul_f32 v[36:37], v[36:37], v[80:81]
	v_pk_mul_f32 v[34:35], v[34:35], v[82:83]
	v_pk_fma_f32 v[12:13], v[32:33], v[36:37], v[12:13]
	v_pk_fma_f32 v[10:11], v[30:31], v[34:35], v[10:11]
	global_store_dwordx4 v[84:85], v[10:13], off offset:1024
	s_nop 0
	v_pk_mul_f32 v[34:35], v[76:77], v[78:79] op_sel_hi:[1,0]
	v_pk_mul_f32 v[36:37], v[74:75], v[78:79] op_sel_hi:[1,0]
	v_mov_b64_e32 v[10:11], v[124:125]
	v_mov_b64_e32 v[12:13], v[126:127]
	v_mov_b64_e32 v[30:31], v[128:129]
	v_mov_b64_e32 v[32:33], v[130:131]
	v_pk_mul_f32 v[30:31], v[30:31], v[34:35]
	v_pk_mul_f32 v[32:33], v[32:33], v[36:37]
	v_pk_fma_f32 v[2:3], v[10:11], v[30:31], v[2:3]
	v_pk_fma_f32 v[4:5], v[12:13], v[32:33], v[4:5]
	global_store_dwordx4 v[84:85], v[2:5], off offset:2048
	s_nop 0
	v_pk_mul_f32 v[30:31], v[70:71], v[78:79] op_sel_hi:[1,0]
	v_pk_mul_f32 v[32:33], v[72:73], v[78:79] op_sel_hi:[1,0]
	s_waitcnt vmcnt(0)
	v_mov_b64_e32 v[72:73], v[62:63]
	v_mov_b64_e32 v[70:71], v[64:65]
	v_mov_b64_e32 v[36:37], v[66:67]
	v_mov_b64_e32 v[34:35], v[68:69]
	v_mov_b64_e32 v[2:3], v[132:133]
	v_mov_b64_e32 v[4:5], v[134:135]
	v_mov_b64_e32 v[10:11], v[136:137]
	v_mov_b64_e32 v[12:13], v[138:139]
	v_pk_mul_f32 v[12:13], v[12:13], v[32:33]
	v_pk_mul_f32 v[10:11], v[10:11], v[30:31]
	v_pk_fma_f32 v[4:5], v[4:5], v[12:13], v[8:9]
	v_pk_fma_f32 v[2:3], v[2:3], v[10:11], v[6:7]
	global_store_dwordx4 v[84:85], v[2:5], off offset:3072
	v_mov_b64_e32 v[32:33], v[16:17]
	v_mov_b64_e32 v[10:11], v[18:19]
	v_mov_b64_e32 v[2:3], v[22:23]
	v_mov_b64_e32 v[6:7], v[26:27]
	v_mov_b64_e32 v[30:31], v[14:15]
	v_mov_b64_e32 v[12:13], v[20:21]
	v_mov_b64_e32 v[4:5], v[24:25]
	v_mov_b64_e32 v[8:9], v[28:29]
	s_andn2_b64 exec, exec, s[12:13]
	s_cbranch_execz .LBB0_65
